# P0 RMSNorm prep loop software-pipelined: next row's 4 loads requested one trip ahead into v44-59, counted vmcnt(4) at top
# speedup vs baseline: 1.0053x; 1.0053x over previous
.LBB0_26:
	s_cmp_lt_i32 s24, 0x8000
	v_lshlrev_b32_e32 v10, 3, v42
	v_lshlrev_b32_e32 v12, 4, v42
	s_cbranch_scc0 .LBB0_31
	v_mbcnt_lo_u32_b32 v0, -1, 0
	v_mbcnt_hi_u32_b32 v0, -1, v0
	v_and_b32_e32 v1, 64, v0
	v_add_u32_e32 v1, 64, v1
	v_xor_b32_e32 v2, 1, v0
	v_cmp_lt_i32_e32 vcc, v2, v1
	s_load_dwordx2 s[10:11], s[0:1], 0xd0
	s_ashr_i32 s3, s8, 31
	v_cndmask_b32_e32 v2, v0, v2, vcc
	v_lshlrev_b32_e32 v4, 2, v2
	v_xor_b32_e32 v2, 2, v0
	v_cmp_lt_i32_e32 vcc, v2, v1
	s_add_u32 s2, s25, s8
	s_addc_u32 s3, 0, s3
	v_cndmask_b32_e32 v2, v0, v2, vcc
	v_lshlrev_b32_e32 v5, 2, v2
	v_xor_b32_e32 v2, 4, v0
	v_cmp_lt_i32_e32 vcc, v2, v1
	s_lshl_b64 s[4:5], s[2:3], 2
	s_waitcnt lgkmcnt(0)
	s_add_u32 s4, s10, s4
	v_cndmask_b32_e32 v2, v0, v2, vcc
	v_lshlrev_b32_e32 v6, 2, v2
	v_xor_b32_e32 v2, 8, v0
	v_cmp_lt_i32_e32 vcc, v2, v1
	s_addc_u32 s5, s11, s5
	s_add_u32 s4, s4, 0x2f00000
	v_cndmask_b32_e32 v2, v0, v2, vcc
	v_lshlrev_b32_e32 v7, 2, v2
	v_xor_b32_e32 v2, 16, v0
	v_cmp_lt_i32_e32 vcc, v2, v1
	v_readlane_b32 s6, v247, 42
	s_addc_u32 s5, s5, 0
	v_cndmask_b32_e32 v2, v0, v2, vcc
	v_readlane_b32 s7, v247, 43
	s_mov_b32 s12, s6
	s_ashr_i32 s13, s6, 31
	v_lshlrev_b32_e32 v9, 2, v2
	v_xor_b32_e32 v2, 32, v0
	s_lshl_b64 s[6:7], s[12:13], 2
	s_lshl_b64 s[8:9], s[2:3], 11
	s_load_dwordx16 s[36:51], s[0:1], 0x0
	v_cmp_lt_i32_e32 vcc, v2, v1
	s_add_u32 s8, s10, s8
	v_mov_b32_e32 v11, 0
	v_cndmask_b32_e32 v0, v0, v2, vcc
	s_addc_u32 s9, s11, s9
	v_lshlrev_b32_e32 v14, 2, v0
	v_lshl_add_u64 v[0:1], s[8:9], 0, v[10:11]
	s_mov_b64 s[8:9], 0x4000400
	v_lshl_add_u64 v[0:1], v[0:1], 0, s[8:9]
	s_lshl_b64 s[8:9], s[12:13], 11
	s_lshl_b64 s[2:3], s[2:3], 12
	s_waitcnt lgkmcnt(0)
	s_add_u32 s2, s36, s2
	v_mov_b32_e32 v13, v11
	s_addc_u32 s3, s37, s3
	v_lshl_add_u64 v[2:3], s[2:3], 0, v[12:13]
	s_mov_b64 s[2:3], 0xc00
	v_lshl_add_u64 v[2:3], v[2:3], 0, s[2:3]
	s_mov_b32 s2, s12
	v_cmp_eq_u32_e32 vcc, 0, v42
	v_writelane_b32 v247, s2, 42
	s_lshl_b64 s[10:11], s[12:13], 12
	v_mov_b32_e32 v13, 0x358637bd
	s_mov_b32 s14, 0x800000
	s_mov_b32 s15, s24
	v_writelane_b32 v247, s3, 43
	global_load_dwordx4 v[44:47], v[2:3], off offset:-3072
	global_load_dwordx4 v[48:51], v[2:3], off offset:-2048
	global_load_dwordx4 v[52:55], v[2:3], off offset:-1024
	global_load_dwordx4 v[56:59], v[2:3], off
	s_waitcnt vmcnt(0)
	s_branch .LBB0_29

.LBB0_29:
	s_waitcnt lgkmcnt(0)
	s_waitcnt vmcnt(4)
	v_mov_b32_e32 v16, v44
	v_mov_b32_e32 v17, v45
	v_mov_b32_e32 v18, v46
	v_mov_b32_e32 v19, v47
	v_mov_b32_e32 v20, v48
	v_mov_b32_e32 v21, v49
	v_mov_b32_e32 v22, v50
	v_mov_b32_e32 v23, v51
	v_mov_b32_e32 v24, v52
	v_mov_b32_e32 v25, v53
	v_mov_b32_e32 v26, v54
	v_mov_b32_e32 v27, v55
	v_mov_b32_e32 v28, v56
	v_mov_b32_e32 v29, v57
	v_mov_b32_e32 v30, v58
	v_mov_b32_e32 v31, v59
	v_readlane_b32 s26, v247, 42
	s_add_i32 s26, s15, s26
	s_cmpk_gt_i32 s26, 0x7fff
	s_cbranch_scc1 .Lmy_prep_go
	v_lshl_add_u64 v[60:61], v[2:3], 0, s[10:11]
	global_load_dwordx4 v[44:47], v[60:61], off offset:-3072
	global_load_dwordx4 v[48:51], v[60:61], off offset:-2048
	global_load_dwordx4 v[52:55], v[60:61], off offset:-1024
	global_load_dwordx4 v[56:59], v[60:61], off
.Lmy_prep_go:
	v_mul_f32_e32 v15, v17, v17
	v_mul_f32_e32 v32, v19, v19
	v_mul_f32_e32 v33, v21, v21
	v_mul_f32_e32 v34, v23, v23
	v_mul_f32_e32 v35, v25, v25
	v_mul_f32_e32 v36, v27, v27
	v_fmac_f32_e32 v15, v16, v16
	v_fmac_f32_e32 v32, v18, v18
	v_fmac_f32_e32 v33, v20, v20
	v_fmac_f32_e32 v34, v22, v22
	v_mul_f32_e32 v37, v29, v29
	v_mul_f32_e32 v38, v31, v31
	v_fmac_f32_e32 v35, v24, v24
	v_fmac_f32_e32 v36, v26, v26
	v_add_f32_e32 v15, v15, v32
	v_add_f32_e32 v32, v33, v34
	v_fmac_f32_e32 v37, v28, v28
	v_fmac_f32_e32 v38, v30, v30
	v_add_f32_e32 v33, v35, v36
	v_add_f32_e32 v15, v15, v32
	v_add_f32_e32 v34, v37, v38
	v_add_f32_e32 v15, v15, v33
	v_add_f32_e32 v15, v15, v34
	ds_bpermute_b32 v32, v4, v15
	v_cvt_pk_bf16_f32 v16, v16, v17
	v_cvt_pk_bf16_f32 v17, v18, v19
	v_cvt_pk_bf16_f32 v18, v20, v21
	v_cvt_pk_bf16_f32 v19, v22, v23
	s_waitcnt lgkmcnt(0)
	v_add_f32_e32 v15, v15, v32
	ds_bpermute_b32 v32, v5, v15
	global_store_dwordx2 v[0:1], v[16:17], off offset:-1024
	global_store_dwordx2 v[0:1], v[18:19], off offset:-512
	v_cvt_pk_bf16_f32 v20, v24, v25
	v_cvt_pk_bf16_f32 v18, v28, v29
	v_cvt_pk_bf16_f32 v19, v30, v31
	s_waitcnt lgkmcnt(0)
	v_add_f32_e32 v15, v15, v32
	ds_bpermute_b32 v32, v6, v15
	global_store_dwordx2 v[0:1], v[18:19], off offset:512
	s_waitcnt lgkmcnt(0)
	v_add_f32_e32 v15, v15, v32
	ds_bpermute_b32 v32, v7, v15
	s_waitcnt lgkmcnt(0)
	v_add_f32_e32 v15, v15, v32
	ds_bpermute_b32 v21, v9, v15
	s_waitcnt lgkmcnt(0)
	v_add_f32_e32 v15, v15, v21
	ds_bpermute_b32 v16, v14, v15
	v_cvt_pk_bf16_f32 v21, v26, v27
	global_store_dwordx2 v[0:1], v[20:21], off
	s_and_saveexec_b64 s[12:13], vcc
	s_cbranch_execz .LBB0_28
	s_waitcnt lgkmcnt(0)
	v_add_f32_e32 v15, v15, v16
	v_fmamk_f32 v15, v15, 0x3a800000, v13
	v_mul_f32_e32 v16, 0x4b800000, v15
	v_cmp_gt_f32_e64 s[2:3], s14, v15
	s_nop 1
	v_cndmask_b32_e64 v15, v15, v16, s[2:3]
	v_rsq_f32_e32 v15, v15
	s_nop 0
	v_mul_f32_e32 v16, 0x45800000, v15
	v_cndmask_b32_e64 v15, v15, v16, s[2:3]
	global_store_dword v11, v15, s[4:5]
	s_branch .LBB0_28
